# g1_pipe3stage
# baseline (speedup 1.0000x reference)
.LBB0_100:
	s_lshl_b32 s0, s78, 9
	s_and_b32 s0, s0, 0xfffff800
	s_lshl_b32 s1, s33, 8
	v_xor_b32_e32 v4, v3, v2
	v_lshlrev_b32_e32 v2, 6, v2
	s_or_b32 s0, s1, s0
	v_and_b32_e32 v131, 48, v4
	v_and_b32_e32 v147, 0x1000, v2
	v_and_b32_e32 v145, 0x3c0, v2
	v_and_b32_e32 v146, 0xffffe000, v2
	v_add_u32_e32 v2, s0, v142
	v_lshlrev_b32_e32 v4, 1, v4
	v_ashrrev_i32_e32 v3, 31, v2
	v_and_b32_e32 v128, 48, v4
	v_lshlrev_b64 v[2:3], 11, v[2:3]
	v_lshl_add_u64 v[0:1], v[0:1], 0, v[128:129]
	v_or_b32_e32 v2, v2, v128
	v_lshl_add_u64 v[134:135], s[20:21], 0, v[0:1]
	v_mov_b32_e32 v0, 0
	s_mov_b32 s70, 1
	v_lshl_add_u64 v[132:133], s[50:51], 0, v[2:3]
	s_mov_b64 s[0:1], 0
	v_mov_b32_e32 v1, v0
	v_mov_b32_e32 v2, v0
	v_mov_b32_e32 v3, v0
	v_mov_b32_e32 v4, v0
	v_mov_b32_e32 v5, v0
	v_mov_b32_e32 v6, v0
	v_mov_b32_e32 v7, v0
	v_mov_b32_e32 v8, v0
	v_mov_b32_e32 v9, v0
	v_mov_b32_e32 v10, v0
	v_mov_b32_e32 v11, v0
	v_mov_b32_e32 v12, v0
	v_mov_b32_e32 v13, v0
	v_mov_b32_e32 v14, v0
	v_mov_b32_e32 v15, v0
	v_mov_b32_e32 v16, v0
	v_mov_b32_e32 v17, v0
	v_mov_b32_e32 v18, v0
	v_mov_b32_e32 v19, v0
	v_mov_b32_e32 v20, v0
	v_mov_b32_e32 v21, v0
	v_mov_b32_e32 v22, v0
	v_mov_b32_e32 v23, v0
	v_mov_b32_e32 v24, v0
	v_mov_b32_e32 v25, v0
	v_mov_b32_e32 v26, v0
	v_mov_b32_e32 v27, v0
	v_mov_b32_e32 v28, v0
	v_mov_b32_e32 v29, v0
	v_mov_b32_e32 v30, v0
	v_mov_b32_e32 v31, v0
	v_mov_b32_e32 v32, v0
	v_mov_b32_e32 v33, v0
	v_mov_b32_e32 v34, v0
	v_mov_b32_e32 v35, v0
	v_mov_b32_e32 v36, v0
	v_mov_b32_e32 v37, v0
	v_mov_b32_e32 v38, v0
	v_mov_b32_e32 v39, v0
	v_mov_b32_e32 v40, v0
	v_mov_b32_e32 v41, v0
	v_mov_b32_e32 v42, v0
	v_mov_b32_e32 v43, v0
	v_mov_b32_e32 v44, v0
	v_mov_b32_e32 v45, v0
	v_mov_b32_e32 v46, v0
	v_mov_b32_e32 v47, v0
	v_mov_b32_e32 v48, v0
	v_mov_b32_e32 v49, v0
	v_mov_b32_e32 v50, v0
	v_mov_b32_e32 v51, v0
	v_mov_b32_e32 v52, v0
	v_mov_b32_e32 v53, v0
	v_mov_b32_e32 v54, v0
	v_mov_b32_e32 v55, v0
	v_mov_b32_e32 v56, v0
	v_mov_b32_e32 v57, v0
	v_mov_b32_e32 v58, v0
	v_mov_b32_e32 v59, v0
	v_mov_b32_e32 v64, v0
	v_mov_b32_e32 v65, v0
	v_mov_b32_e32 v66, v0
	v_mov_b32_e32 v67, v0
	v_mov_b32_e32 v60, v0
	v_mov_b32_e32 v61, v0
	v_mov_b32_e32 v62, v0
	v_mov_b32_e32 v63, v0
	v_mov_b32_e32 v68, v0
	v_mov_b32_e32 v69, v0
	v_mov_b32_e32 v70, v0
	v_mov_b32_e32 v71, v0
	v_mov_b32_e32 v72, v0
	v_mov_b32_e32 v73, v0
	v_mov_b32_e32 v74, v0
	v_mov_b32_e32 v75, v0
	v_mov_b32_e32 v76, v0
	v_mov_b32_e32 v77, v0
	v_mov_b32_e32 v78, v0
	v_mov_b32_e32 v79, v0
	v_mov_b32_e32 v80, v0
	v_mov_b32_e32 v81, v0
	v_mov_b32_e32 v82, v0
	v_mov_b32_e32 v83, v0
	v_mov_b32_e32 v84, v0
	v_mov_b32_e32 v85, v0
	v_mov_b32_e32 v86, v0
	v_mov_b32_e32 v87, v0
	v_mov_b32_e32 v88, v0
	v_mov_b32_e32 v89, v0
	v_mov_b32_e32 v90, v0
	v_mov_b32_e32 v91, v0
	v_mov_b32_e32 v92, v0
	v_mov_b32_e32 v93, v0
	v_mov_b32_e32 v94, v0
	v_mov_b32_e32 v95, v0
	v_mov_b32_e32 v96, v0
	v_mov_b32_e32 v97, v0
	v_mov_b32_e32 v98, v0
	v_mov_b32_e32 v99, v0
	v_mov_b32_e32 v100, v0
	v_mov_b32_e32 v101, v0
	v_mov_b32_e32 v102, v0
	v_mov_b32_e32 v103, v0
	v_mov_b32_e32 v104, v0
	v_mov_b32_e32 v105, v0
	v_mov_b32_e32 v106, v0
	v_mov_b32_e32 v107, v0
	v_mov_b32_e32 v108, v0
	v_mov_b32_e32 v109, v0
	v_mov_b32_e32 v110, v0
	v_mov_b32_e32 v111, v0
	v_mov_b32_e32 v112, v0
	v_mov_b32_e32 v113, v0
	v_mov_b32_e32 v114, v0
	v_mov_b32_e32 v115, v0
	v_mov_b32_e32 v116, v0
	v_mov_b32_e32 v117, v0
	v_mov_b32_e32 v118, v0
	v_mov_b32_e32 v119, v0
	v_mov_b32_e32 v120, v0
	v_mov_b32_e32 v121, v0
	v_mov_b32_e32 v122, v0
	v_mov_b32_e32 v123, v0
	v_mov_b32_e32 v124, v0
	v_mov_b32_e32 v125, v0
	v_mov_b32_e32 v126, v0
	v_mov_b32_e32 v127, v0
	v_lshl_add_u64 v[226:227], v[132:133], 0, 64
	v_lshl_add_u64 v[228:229], v[132:133], 0, s[12:13]
	v_lshl_add_u64 v[230:231], v[132:133], 0, s[14:15]
	v_lshl_add_u64 v[232:233], v[132:133], 0, s[16:17]
	v_lshl_add_u64 v[234:235], v[134:135], 0, s[34:35]
	v_lshl_add_u64 v[236:237], v[134:135], 0, s[46:47]
	v_add3_u32 v216, v146, v145, v131
	v_add3_u32 v217, v147, v145, v131
	v_readfirstlane_b32 s30, v144
	s_nop 3
	s_add_u32 s24, s30, 0x6000
	s_mov_b32 m0, s24
	s_nop 0
	global_load_lds_dwordx4 v[226:227], off
	v_lshl_add_u64 v[226:227], v[226:227], 0, 64
	s_nop 0
	s_add_u32 s97, s24, 0x1000
	s_mov_b32 m0, s97
	s_nop 0
	global_load_lds_dwordx4 v[228:229], off
	v_lshl_add_u64 v[228:229], v[228:229], 0, 64
	s_nop 0
	s_add_u32 s97, s24, 0x2000
	s_mov_b32 m0, s97
	s_nop 0
	global_load_lds_dwordx4 v[230:231], off
	v_lshl_add_u64 v[230:231], v[230:231], 0, 64
	s_nop 0
	s_add_u32 s97, s24, 0x3000
	s_mov_b32 m0, s97
	s_nop 0
	global_load_lds_dwordx4 v[232:233], off
	v_lshl_add_u64 v[232:233], v[232:233], 0, 64
	s_nop 0
	s_add_u32 s97, s24, 0x4000
	s_mov_b32 m0, s97
	s_nop 0
	global_load_lds_dwordx4 v[234:235], off
	v_lshl_add_u64 v[234:235], v[234:235], 0, 64
	s_nop 0
	s_add_u32 s97, s24, 0x5000
	s_mov_b32 m0, s97
	s_nop 0
	global_load_lds_dwordx4 v[236:237], off
	v_lshl_add_u64 v[236:237], v[236:237], 0, 64
	s_nop 0
	s_add_u32 s24, s30, 0xc000
	s_mov_b32 m0, s24
	s_nop 0
	global_load_lds_dwordx4 v[226:227], off
	v_lshl_add_u64 v[226:227], v[226:227], 0, 64
	s_nop 0
	s_add_u32 s97, s24, 0x1000
	s_mov_b32 m0, s97
	s_nop 0
	global_load_lds_dwordx4 v[228:229], off
	v_lshl_add_u64 v[228:229], v[228:229], 0, 64
	s_nop 0
	s_add_u32 s97, s24, 0x2000
	s_mov_b32 m0, s97
	s_nop 0
	global_load_lds_dwordx4 v[230:231], off
	v_lshl_add_u64 v[230:231], v[230:231], 0, 64
	s_nop 0
	s_add_u32 s97, s24, 0x3000
	s_mov_b32 m0, s97
	s_nop 0
	global_load_lds_dwordx4 v[232:233], off
	v_lshl_add_u64 v[232:233], v[232:233], 0, 64
	s_nop 0
	s_add_u32 s97, s24, 0x4000
	s_mov_b32 m0, s97
	s_nop 0
	global_load_lds_dwordx4 v[234:235], off
	v_lshl_add_u64 v[234:235], v[234:235], 0, 64
	s_nop 0
	s_add_u32 s97, s24, 0x5000
	s_mov_b32 m0, s97
	s_nop 0
	global_load_lds_dwordx4 v[236:237], off
	v_lshl_add_u64 v[236:237], v[236:237], 0, 64
	s_nop 0
	s_waitcnt vmcnt(12) lgkmcnt(0)
	s_barrier
	ds_read_b128 v[148:151], v217 offset:16384
	ds_read_b128 v[152:155], v217 offset:17408
	ds_read_b128 v[156:159], v217 offset:18432
	ds_read_b128 v[160:163], v217 offset:19456
	ds_read_b128 v[164:167], v216 offset:0
	ds_read_b128 v[168:171], v216 offset:1024
	ds_read_b128 v[172:175], v216 offset:2048
	ds_read_b128 v[176:179], v216 offset:3072
	s_mov_b32 s18, 0
	s_movk_i32 s25, 0x6000
	s_mov_b32 s32, 0xc000
	s_mov_b32 s70, 0
.Lg1_loop:
	v_add_u32_e32 v218, s18, v216
	ds_read_b128 v[184:187], v218 offset:4096
	ds_read_b128 v[188:191], v218 offset:5120
	ds_read_b128 v[192:195], v218 offset:6144
	ds_read_b128 v[196:199], v218 offset:7168
	v_add_u32_e32 v219, s25, v216
	v_add_u32_e32 v220, s25, v217
	s_waitcnt lgkmcnt(7)
	v_mfma_f32_16x16x32_bf16 v[124:127], v[148:151], v[164:167], v[124:127]
	v_mfma_f32_16x16x32_bf16 v[120:123], v[152:155], v[164:167], v[120:123]
	v_mfma_f32_16x16x32_bf16 v[116:119], v[156:159], v[164:167], v[116:119]
	v_mfma_f32_16x16x32_bf16 v[112:115], v[160:163], v[164:167], v[112:115]
	s_waitcnt lgkmcnt(6)
	v_mfma_f32_16x16x32_bf16 v[108:111], v[148:151], v[168:171], v[108:111]
	v_mfma_f32_16x16x32_bf16 v[104:107], v[152:155], v[168:171], v[104:107]
	v_mfma_f32_16x16x32_bf16 v[100:103], v[156:159], v[168:171], v[100:103]
	v_mfma_f32_16x16x32_bf16 v[96:99], v[160:163], v[168:171], v[96:99]
	s_waitcnt lgkmcnt(5)
	v_mfma_f32_16x16x32_bf16 v[92:95], v[148:151], v[172:175], v[92:95]
	v_mfma_f32_16x16x32_bf16 v[88:91], v[152:155], v[172:175], v[88:91]
	v_mfma_f32_16x16x32_bf16 v[84:87], v[156:159], v[172:175], v[84:87]
	v_mfma_f32_16x16x32_bf16 v[80:83], v[160:163], v[172:175], v[80:83]
	s_waitcnt lgkmcnt(4)
	v_mfma_f32_16x16x32_bf16 v[76:79], v[148:151], v[176:179], v[76:79]
	v_mfma_f32_16x16x32_bf16 v[72:75], v[152:155], v[176:179], v[72:75]
	v_mfma_f32_16x16x32_bf16 v[68:71], v[156:159], v[176:179], v[68:71]
	v_mfma_f32_16x16x32_bf16 v[60:63], v[160:163], v[176:179], v[60:63]
	s_waitcnt vmcnt(6) lgkmcnt(0)
	s_barrier
	v_mfma_f32_16x16x32_bf16 v[64:67], v[148:151], v[184:187], v[64:67]
	s_add_u32 s24, s18, s30
	s_mov_b32 m0, s24
	ds_read_b128 v[200:203], v220 offset:16384
	v_mfma_f32_16x16x32_bf16 v[56:59], v[152:155], v[184:187], v[56:59]
	global_load_lds_dwordx4 v[226:227], off
	v_lshl_add_u64 v[226:227], v[226:227], 0, 64
	ds_read_b128 v[204:207], v220 offset:17408
	v_mfma_f32_16x16x32_bf16 v[52:55], v[156:159], v[184:187], v[52:55]
	s_add_u32 s97, s24, 0x1000
	s_mov_b32 m0, s97
	ds_read_b128 v[208:211], v220 offset:18432
	v_mfma_f32_16x16x32_bf16 v[48:51], v[160:163], v[184:187], v[48:51]
	global_load_lds_dwordx4 v[228:229], off
	v_lshl_add_u64 v[228:229], v[228:229], 0, 64
	ds_read_b128 v[212:215], v220 offset:19456
	v_mfma_f32_16x16x32_bf16 v[44:47], v[148:151], v[188:191], v[44:47]
	s_add_u32 s97, s24, 0x2000
	s_mov_b32 m0, s97
	ds_read_b128 v[164:167], v219 offset:0
	v_mfma_f32_16x16x32_bf16 v[40:43], v[152:155], v[188:191], v[40:43]
	global_load_lds_dwordx4 v[230:231], off
	v_lshl_add_u64 v[230:231], v[230:231], 0, 64
	ds_read_b128 v[168:171], v219 offset:1024
	v_mfma_f32_16x16x32_bf16 v[36:39], v[156:159], v[188:191], v[36:39]
	s_add_u32 s97, s24, 0x3000
	s_mov_b32 m0, s97
	ds_read_b128 v[172:175], v219 offset:2048
	v_mfma_f32_16x16x32_bf16 v[32:35], v[160:163], v[188:191], v[32:35]
	global_load_lds_dwordx4 v[232:233], off
	v_lshl_add_u64 v[232:233], v[232:233], 0, 64
	ds_read_b128 v[176:179], v219 offset:3072
	v_mfma_f32_16x16x32_bf16 v[28:31], v[148:151], v[192:195], v[28:31]
	s_add_u32 s97, s24, 0x4000
	s_mov_b32 m0, s97
	v_mfma_f32_16x16x32_bf16 v[24:27], v[152:155], v[192:195], v[24:27]
	global_load_lds_dwordx4 v[234:235], off
	v_lshl_add_u64 v[234:235], v[234:235], 0, 64
	v_mfma_f32_16x16x32_bf16 v[20:23], v[156:159], v[192:195], v[20:23]
	s_add_u32 s97, s24, 0x5000
	s_mov_b32 m0, s97
	v_mfma_f32_16x16x32_bf16 v[16:19], v[160:163], v[192:195], v[16:19]
	global_load_lds_dwordx4 v[236:237], off
	v_lshl_add_u64 v[236:237], v[236:237], 0, 64
	v_mfma_f32_16x16x32_bf16 v[12:15], v[148:151], v[196:199], v[12:15]
	v_mfma_f32_16x16x32_bf16 v[8:11], v[152:155], v[196:199], v[8:11]
	v_mfma_f32_16x16x32_bf16 v[4:7], v[156:159], v[196:199], v[4:7]
	v_mfma_f32_16x16x32_bf16 v[0:3], v[160:163], v[196:199], v[0:3]
	s_mov_b32 s24, s18
	s_mov_b32 s18, s25
	s_mov_b32 s25, s32
	s_mov_b32 s32, s24
	v_add_u32_e32 v218, s18, v216
	ds_read_b128 v[184:187], v218 offset:4096
	ds_read_b128 v[188:191], v218 offset:5120
	ds_read_b128 v[192:195], v218 offset:6144
	ds_read_b128 v[196:199], v218 offset:7168
	v_add_u32_e32 v219, s25, v216
	v_add_u32_e32 v220, s25, v217
	s_waitcnt lgkmcnt(7)
	v_mfma_f32_16x16x32_bf16 v[124:127], v[200:203], v[164:167], v[124:127]
	v_mfma_f32_16x16x32_bf16 v[120:123], v[204:207], v[164:167], v[120:123]
	v_mfma_f32_16x16x32_bf16 v[116:119], v[208:211], v[164:167], v[116:119]
	v_mfma_f32_16x16x32_bf16 v[112:115], v[212:215], v[164:167], v[112:115]
	s_waitcnt lgkmcnt(6)
	v_mfma_f32_16x16x32_bf16 v[108:111], v[200:203], v[168:171], v[108:111]
	v_mfma_f32_16x16x32_bf16 v[104:107], v[204:207], v[168:171], v[104:107]
	v_mfma_f32_16x16x32_bf16 v[100:103], v[208:211], v[168:171], v[100:103]
	v_mfma_f32_16x16x32_bf16 v[96:99], v[212:215], v[168:171], v[96:99]
	s_waitcnt lgkmcnt(5)
	v_mfma_f32_16x16x32_bf16 v[92:95], v[200:203], v[172:175], v[92:95]
	v_mfma_f32_16x16x32_bf16 v[88:91], v[204:207], v[172:175], v[88:91]
	v_mfma_f32_16x16x32_bf16 v[84:87], v[208:211], v[172:175], v[84:87]
	v_mfma_f32_16x16x32_bf16 v[80:83], v[212:215], v[172:175], v[80:83]
	s_waitcnt lgkmcnt(4)
	v_mfma_f32_16x16x32_bf16 v[76:79], v[200:203], v[176:179], v[76:79]
	v_mfma_f32_16x16x32_bf16 v[72:75], v[204:207], v[176:179], v[72:75]
	v_mfma_f32_16x16x32_bf16 v[68:71], v[208:211], v[176:179], v[68:71]
	v_mfma_f32_16x16x32_bf16 v[60:63], v[212:215], v[176:179], v[60:63]
	s_waitcnt vmcnt(6) lgkmcnt(0)
	s_barrier
	v_mfma_f32_16x16x32_bf16 v[64:67], v[200:203], v[184:187], v[64:67]
	s_add_u32 s24, s18, s30
	s_mov_b32 m0, s24
	ds_read_b128 v[148:151], v220 offset:16384
	v_mfma_f32_16x16x32_bf16 v[56:59], v[204:207], v[184:187], v[56:59]
	global_load_lds_dwordx4 v[226:227], off
	v_lshl_add_u64 v[226:227], v[226:227], 0, 64
	ds_read_b128 v[152:155], v220 offset:17408
	v_mfma_f32_16x16x32_bf16 v[52:55], v[208:211], v[184:187], v[52:55]
	s_add_u32 s97, s24, 0x1000
	s_mov_b32 m0, s97
	ds_read_b128 v[156:159], v220 offset:18432
	v_mfma_f32_16x16x32_bf16 v[48:51], v[212:215], v[184:187], v[48:51]
	global_load_lds_dwordx4 v[228:229], off
	v_lshl_add_u64 v[228:229], v[228:229], 0, 64
	ds_read_b128 v[160:163], v220 offset:19456
	v_mfma_f32_16x16x32_bf16 v[44:47], v[200:203], v[188:191], v[44:47]
	s_add_u32 s97, s24, 0x2000
	s_mov_b32 m0, s97
	ds_read_b128 v[164:167], v219 offset:0
	v_mfma_f32_16x16x32_bf16 v[40:43], v[204:207], v[188:191], v[40:43]
	global_load_lds_dwordx4 v[230:231], off
	v_lshl_add_u64 v[230:231], v[230:231], 0, 64
	ds_read_b128 v[168:171], v219 offset:1024
	v_mfma_f32_16x16x32_bf16 v[36:39], v[208:211], v[188:191], v[36:39]
	s_add_u32 s97, s24, 0x3000
	s_mov_b32 m0, s97
	ds_read_b128 v[172:175], v219 offset:2048
	v_mfma_f32_16x16x32_bf16 v[32:35], v[212:215], v[188:191], v[32:35]
	global_load_lds_dwordx4 v[232:233], off
	v_lshl_add_u64 v[232:233], v[232:233], 0, 64
	ds_read_b128 v[176:179], v219 offset:3072
	v_mfma_f32_16x16x32_bf16 v[28:31], v[200:203], v[192:195], v[28:31]
	s_add_u32 s97, s24, 0x4000
	s_mov_b32 m0, s97
	v_mfma_f32_16x16x32_bf16 v[24:27], v[204:207], v[192:195], v[24:27]
	global_load_lds_dwordx4 v[234:235], off
	v_lshl_add_u64 v[234:235], v[234:235], 0, 64
	v_mfma_f32_16x16x32_bf16 v[20:23], v[208:211], v[192:195], v[20:23]
	s_add_u32 s97, s24, 0x5000
	s_mov_b32 m0, s97
	v_mfma_f32_16x16x32_bf16 v[16:19], v[212:215], v[192:195], v[16:19]
	global_load_lds_dwordx4 v[236:237], off
	v_lshl_add_u64 v[236:237], v[236:237], 0, 64
	v_mfma_f32_16x16x32_bf16 v[12:15], v[200:203], v[196:199], v[12:15]
	v_mfma_f32_16x16x32_bf16 v[8:11], v[204:207], v[196:199], v[8:11]
	v_mfma_f32_16x16x32_bf16 v[4:7], v[208:211], v[196:199], v[4:7]
	v_mfma_f32_16x16x32_bf16 v[0:3], v[212:215], v[196:199], v[0:3]
	s_mov_b32 s24, s18
	s_mov_b32 s18, s25
	s_mov_b32 s25, s32
	s_mov_b32 s32, s24
	s_add_i32 s70, s70, 1
	s_cmp_lt_u32 s70, 14
	s_cbranch_scc1 .Lg1_loop
	v_add_u32_e32 v218, s18, v216
	ds_read_b128 v[184:187], v218 offset:4096
	ds_read_b128 v[188:191], v218 offset:5120
	ds_read_b128 v[192:195], v218 offset:6144
	ds_read_b128 v[196:199], v218 offset:7168
	v_add_u32_e32 v219, s25, v216
	v_add_u32_e32 v220, s25, v217
	s_waitcnt lgkmcnt(7)
	v_mfma_f32_16x16x32_bf16 v[124:127], v[148:151], v[164:167], v[124:127]
	v_mfma_f32_16x16x32_bf16 v[120:123], v[152:155], v[164:167], v[120:123]
	v_mfma_f32_16x16x32_bf16 v[116:119], v[156:159], v[164:167], v[116:119]
	v_mfma_f32_16x16x32_bf16 v[112:115], v[160:163], v[164:167], v[112:115]
	s_waitcnt lgkmcnt(6)
	v_mfma_f32_16x16x32_bf16 v[108:111], v[148:151], v[168:171], v[108:111]
	v_mfma_f32_16x16x32_bf16 v[104:107], v[152:155], v[168:171], v[104:107]
	v_mfma_f32_16x16x32_bf16 v[100:103], v[156:159], v[168:171], v[100:103]
	v_mfma_f32_16x16x32_bf16 v[96:99], v[160:163], v[168:171], v[96:99]
	s_waitcnt lgkmcnt(5)
	v_mfma_f32_16x16x32_bf16 v[92:95], v[148:151], v[172:175], v[92:95]
	v_mfma_f32_16x16x32_bf16 v[88:91], v[152:155], v[172:175], v[88:91]
	v_mfma_f32_16x16x32_bf16 v[84:87], v[156:159], v[172:175], v[84:87]
	v_mfma_f32_16x16x32_bf16 v[80:83], v[160:163], v[172:175], v[80:83]
	s_waitcnt lgkmcnt(4)
	v_mfma_f32_16x16x32_bf16 v[76:79], v[148:151], v[176:179], v[76:79]
	v_mfma_f32_16x16x32_bf16 v[72:75], v[152:155], v[176:179], v[72:75]
	v_mfma_f32_16x16x32_bf16 v[68:71], v[156:159], v[176:179], v[68:71]
	v_mfma_f32_16x16x32_bf16 v[60:63], v[160:163], v[176:179], v[60:63]
	s_waitcnt vmcnt(6) lgkmcnt(0)
	s_barrier
	v_mfma_f32_16x16x32_bf16 v[64:67], v[148:151], v[184:187], v[64:67]
	s_add_u32 s24, s18, s30
	s_mov_b32 m0, s24
	ds_read_b128 v[200:203], v220 offset:16384
	v_mfma_f32_16x16x32_bf16 v[56:59], v[152:155], v[184:187], v[56:59]
	global_load_lds_dwordx4 v[226:227], off
	v_lshl_add_u64 v[226:227], v[226:227], 0, 64
	ds_read_b128 v[204:207], v220 offset:17408
	v_mfma_f32_16x16x32_bf16 v[52:55], v[156:159], v[184:187], v[52:55]
	s_add_u32 s97, s24, 0x1000
	s_mov_b32 m0, s97
	ds_read_b128 v[208:211], v220 offset:18432
	v_mfma_f32_16x16x32_bf16 v[48:51], v[160:163], v[184:187], v[48:51]
	global_load_lds_dwordx4 v[228:229], off
	v_lshl_add_u64 v[228:229], v[228:229], 0, 64
	ds_read_b128 v[212:215], v220 offset:19456
	v_mfma_f32_16x16x32_bf16 v[44:47], v[148:151], v[188:191], v[44:47]
	s_add_u32 s97, s24, 0x2000
	s_mov_b32 m0, s97
	ds_read_b128 v[164:167], v219 offset:0
	v_mfma_f32_16x16x32_bf16 v[40:43], v[152:155], v[188:191], v[40:43]
	global_load_lds_dwordx4 v[230:231], off
	v_lshl_add_u64 v[230:231], v[230:231], 0, 64
	ds_read_b128 v[168:171], v219 offset:1024
	v_mfma_f32_16x16x32_bf16 v[36:39], v[156:159], v[188:191], v[36:39]
	s_add_u32 s97, s24, 0x3000
	s_mov_b32 m0, s97
	ds_read_b128 v[172:175], v219 offset:2048
	v_mfma_f32_16x16x32_bf16 v[32:35], v[160:163], v[188:191], v[32:35]
	global_load_lds_dwordx4 v[232:233], off
	v_lshl_add_u64 v[232:233], v[232:233], 0, 64
	ds_read_b128 v[176:179], v219 offset:3072
	v_mfma_f32_16x16x32_bf16 v[28:31], v[148:151], v[192:195], v[28:31]
	s_add_u32 s97, s24, 0x4000
	s_mov_b32 m0, s97
	v_mfma_f32_16x16x32_bf16 v[24:27], v[152:155], v[192:195], v[24:27]
	global_load_lds_dwordx4 v[234:235], off
	v_lshl_add_u64 v[234:235], v[234:235], 0, 64
	v_mfma_f32_16x16x32_bf16 v[20:23], v[156:159], v[192:195], v[20:23]
	s_add_u32 s97, s24, 0x5000
	s_mov_b32 m0, s97
	v_mfma_f32_16x16x32_bf16 v[16:19], v[160:163], v[192:195], v[16:19]
	global_load_lds_dwordx4 v[236:237], off
	v_lshl_add_u64 v[236:237], v[236:237], 0, 64
	v_mfma_f32_16x16x32_bf16 v[12:15], v[148:151], v[196:199], v[12:15]
	v_mfma_f32_16x16x32_bf16 v[8:11], v[152:155], v[196:199], v[8:11]
	v_mfma_f32_16x16x32_bf16 v[4:7], v[156:159], v[196:199], v[4:7]
	v_mfma_f32_16x16x32_bf16 v[0:3], v[160:163], v[196:199], v[0:3]
	s_mov_b32 s24, s18
	s_mov_b32 s18, s25
	s_mov_b32 s25, s32
	s_mov_b32 s32, s24
	v_add_u32_e32 v218, s18, v216
	ds_read_b128 v[184:187], v218 offset:4096
	ds_read_b128 v[188:191], v218 offset:5120
	ds_read_b128 v[192:195], v218 offset:6144
	ds_read_b128 v[196:199], v218 offset:7168
	v_add_u32_e32 v219, s25, v216
	v_add_u32_e32 v220, s25, v217
	s_waitcnt lgkmcnt(7)
	v_mfma_f32_16x16x32_bf16 v[124:127], v[200:203], v[164:167], v[124:127]
	v_mfma_f32_16x16x32_bf16 v[120:123], v[204:207], v[164:167], v[120:123]
	v_mfma_f32_16x16x32_bf16 v[116:119], v[208:211], v[164:167], v[116:119]
	v_mfma_f32_16x16x32_bf16 v[112:115], v[212:215], v[164:167], v[112:115]
	s_waitcnt lgkmcnt(6)
	v_mfma_f32_16x16x32_bf16 v[108:111], v[200:203], v[168:171], v[108:111]
	v_mfma_f32_16x16x32_bf16 v[104:107], v[204:207], v[168:171], v[104:107]
	v_mfma_f32_16x16x32_bf16 v[100:103], v[208:211], v[168:171], v[100:103]
	v_mfma_f32_16x16x32_bf16 v[96:99], v[212:215], v[168:171], v[96:99]
	s_waitcnt lgkmcnt(5)
	v_mfma_f32_16x16x32_bf16 v[92:95], v[200:203], v[172:175], v[92:95]
	v_mfma_f32_16x16x32_bf16 v[88:91], v[204:207], v[172:175], v[88:91]
	v_mfma_f32_16x16x32_bf16 v[84:87], v[208:211], v[172:175], v[84:87]
	v_mfma_f32_16x16x32_bf16 v[80:83], v[212:215], v[172:175], v[80:83]
	s_waitcnt lgkmcnt(4)
	v_mfma_f32_16x16x32_bf16 v[76:79], v[200:203], v[176:179], v[76:79]
	v_mfma_f32_16x16x32_bf16 v[72:75], v[204:207], v[176:179], v[72:75]
	v_mfma_f32_16x16x32_bf16 v[68:71], v[208:211], v[176:179], v[68:71]
	v_mfma_f32_16x16x32_bf16 v[60:63], v[212:215], v[176:179], v[60:63]
	s_waitcnt vmcnt(6) lgkmcnt(0)
	s_barrier
	v_mfma_f32_16x16x32_bf16 v[64:67], v[200:203], v[184:187], v[64:67]
	ds_read_b128 v[148:151], v220 offset:16384
	v_mfma_f32_16x16x32_bf16 v[56:59], v[204:207], v[184:187], v[56:59]
	ds_read_b128 v[152:155], v220 offset:17408
	v_mfma_f32_16x16x32_bf16 v[52:55], v[208:211], v[184:187], v[52:55]
	ds_read_b128 v[156:159], v220 offset:18432
	v_mfma_f32_16x16x32_bf16 v[48:51], v[212:215], v[184:187], v[48:51]
	ds_read_b128 v[160:163], v220 offset:19456
	v_mfma_f32_16x16x32_bf16 v[44:47], v[200:203], v[188:191], v[44:47]
	ds_read_b128 v[164:167], v219 offset:0
	v_mfma_f32_16x16x32_bf16 v[40:43], v[204:207], v[188:191], v[40:43]
	ds_read_b128 v[168:171], v219 offset:1024
	v_mfma_f32_16x16x32_bf16 v[36:39], v[208:211], v[188:191], v[36:39]
	ds_read_b128 v[172:175], v219 offset:2048
	v_mfma_f32_16x16x32_bf16 v[32:35], v[212:215], v[188:191], v[32:35]
	ds_read_b128 v[176:179], v219 offset:3072
	v_mfma_f32_16x16x32_bf16 v[28:31], v[200:203], v[192:195], v[28:31]
	v_mfma_f32_16x16x32_bf16 v[24:27], v[204:207], v[192:195], v[24:27]
	v_mfma_f32_16x16x32_bf16 v[20:23], v[208:211], v[192:195], v[20:23]
	v_mfma_f32_16x16x32_bf16 v[16:19], v[212:215], v[192:195], v[16:19]
	v_mfma_f32_16x16x32_bf16 v[12:15], v[200:203], v[196:199], v[12:15]
	v_mfma_f32_16x16x32_bf16 v[8:11], v[204:207], v[196:199], v[8:11]
	v_mfma_f32_16x16x32_bf16 v[4:7], v[208:211], v[196:199], v[4:7]
	v_mfma_f32_16x16x32_bf16 v[0:3], v[212:215], v[196:199], v[0:3]
	s_mov_b32 s24, s18
	s_mov_b32 s18, s25
	s_mov_b32 s25, s32
	s_mov_b32 s32, s24
	v_add_u32_e32 v218, s18, v216
	ds_read_b128 v[184:187], v218 offset:4096
	ds_read_b128 v[188:191], v218 offset:5120
	ds_read_b128 v[192:195], v218 offset:6144
	ds_read_b128 v[196:199], v218 offset:7168
	v_add_u32_e32 v219, s25, v216
	v_add_u32_e32 v220, s25, v217
	s_waitcnt lgkmcnt(7)
	v_mfma_f32_16x16x32_bf16 v[124:127], v[148:151], v[164:167], v[124:127]
	v_mfma_f32_16x16x32_bf16 v[120:123], v[152:155], v[164:167], v[120:123]
	v_mfma_f32_16x16x32_bf16 v[116:119], v[156:159], v[164:167], v[116:119]
	v_mfma_f32_16x16x32_bf16 v[112:115], v[160:163], v[164:167], v[112:115]
	s_waitcnt lgkmcnt(6)
	v_mfma_f32_16x16x32_bf16 v[108:111], v[148:151], v[168:171], v[108:111]
	v_mfma_f32_16x16x32_bf16 v[104:107], v[152:155], v[168:171], v[104:107]
	v_mfma_f32_16x16x32_bf16 v[100:103], v[156:159], v[168:171], v[100:103]
	v_mfma_f32_16x16x32_bf16 v[96:99], v[160:163], v[168:171], v[96:99]
	s_waitcnt lgkmcnt(5)
	v_mfma_f32_16x16x32_bf16 v[92:95], v[148:151], v[172:175], v[92:95]
	v_mfma_f32_16x16x32_bf16 v[88:91], v[152:155], v[172:175], v[88:91]
	v_mfma_f32_16x16x32_bf16 v[84:87], v[156:159], v[172:175], v[84:87]
	v_mfma_f32_16x16x32_bf16 v[80:83], v[160:163], v[172:175], v[80:83]
	s_waitcnt lgkmcnt(4)
	v_mfma_f32_16x16x32_bf16 v[76:79], v[148:151], v[176:179], v[76:79]
	v_mfma_f32_16x16x32_bf16 v[72:75], v[152:155], v[176:179], v[72:75]
	v_mfma_f32_16x16x32_bf16 v[68:71], v[156:159], v[176:179], v[68:71]
	v_mfma_f32_16x16x32_bf16 v[60:63], v[160:163], v[176:179], v[60:63]
	s_waitcnt vmcnt(0) lgkmcnt(0)
	s_barrier
	v_mfma_f32_16x16x32_bf16 v[64:67], v[148:151], v[184:187], v[64:67]
	ds_read_b128 v[200:203], v220 offset:16384
	v_mfma_f32_16x16x32_bf16 v[56:59], v[152:155], v[184:187], v[56:59]
	ds_read_b128 v[204:207], v220 offset:17408
	v_mfma_f32_16x16x32_bf16 v[52:55], v[156:159], v[184:187], v[52:55]
	ds_read_b128 v[208:211], v220 offset:18432
	v_mfma_f32_16x16x32_bf16 v[48:51], v[160:163], v[184:187], v[48:51]
	ds_read_b128 v[212:215], v220 offset:19456
	v_mfma_f32_16x16x32_bf16 v[44:47], v[148:151], v[188:191], v[44:47]
	ds_read_b128 v[164:167], v219 offset:0
	v_mfma_f32_16x16x32_bf16 v[40:43], v[152:155], v[188:191], v[40:43]
	ds_read_b128 v[168:171], v219 offset:1024
	v_mfma_f32_16x16x32_bf16 v[36:39], v[156:159], v[188:191], v[36:39]
	ds_read_b128 v[172:175], v219 offset:2048
	v_mfma_f32_16x16x32_bf16 v[32:35], v[160:163], v[188:191], v[32:35]
	ds_read_b128 v[176:179], v219 offset:3072
	v_mfma_f32_16x16x32_bf16 v[28:31], v[148:151], v[192:195], v[28:31]
	v_mfma_f32_16x16x32_bf16 v[24:27], v[152:155], v[192:195], v[24:27]
	v_mfma_f32_16x16x32_bf16 v[20:23], v[156:159], v[192:195], v[20:23]
	v_mfma_f32_16x16x32_bf16 v[16:19], v[160:163], v[192:195], v[16:19]
	v_mfma_f32_16x16x32_bf16 v[12:15], v[148:151], v[196:199], v[12:15]
	v_mfma_f32_16x16x32_bf16 v[8:11], v[152:155], v[196:199], v[8:11]
	v_mfma_f32_16x16x32_bf16 v[4:7], v[156:159], v[196:199], v[4:7]
	v_mfma_f32_16x16x32_bf16 v[0:3], v[160:163], v[196:199], v[0:3]
	s_mov_b32 s24, s18
	s_mov_b32 s18, s25
	s_mov_b32 s25, s32
	s_mov_b32 s32, s24
	v_add_u32_e32 v218, s18, v216
	ds_read_b128 v[184:187], v218 offset:4096
	ds_read_b128 v[188:191], v218 offset:5120
	ds_read_b128 v[192:195], v218 offset:6144
	ds_read_b128 v[196:199], v218 offset:7168
	s_waitcnt lgkmcnt(7)
	v_mfma_f32_16x16x32_bf16 v[124:127], v[200:203], v[164:167], v[124:127]
	v_mfma_f32_16x16x32_bf16 v[120:123], v[204:207], v[164:167], v[120:123]
	v_mfma_f32_16x16x32_bf16 v[116:119], v[208:211], v[164:167], v[116:119]
	v_mfma_f32_16x16x32_bf16 v[112:115], v[212:215], v[164:167], v[112:115]
	s_waitcnt lgkmcnt(6)
	v_mfma_f32_16x16x32_bf16 v[108:111], v[200:203], v[168:171], v[108:111]
	v_mfma_f32_16x16x32_bf16 v[104:107], v[204:207], v[168:171], v[104:107]
	v_mfma_f32_16x16x32_bf16 v[100:103], v[208:211], v[168:171], v[100:103]
	v_mfma_f32_16x16x32_bf16 v[96:99], v[212:215], v[168:171], v[96:99]
	s_waitcnt lgkmcnt(5)
	v_mfma_f32_16x16x32_bf16 v[92:95], v[200:203], v[172:175], v[92:95]
	v_mfma_f32_16x16x32_bf16 v[88:91], v[204:207], v[172:175], v[88:91]
	v_mfma_f32_16x16x32_bf16 v[84:87], v[208:211], v[172:175], v[84:87]
	v_mfma_f32_16x16x32_bf16 v[80:83], v[212:215], v[172:175], v[80:83]
	s_waitcnt lgkmcnt(4)
	v_mfma_f32_16x16x32_bf16 v[76:79], v[200:203], v[176:179], v[76:79]
	v_mfma_f32_16x16x32_bf16 v[72:75], v[204:207], v[176:179], v[72:75]
	v_mfma_f32_16x16x32_bf16 v[68:71], v[208:211], v[176:179], v[68:71]
	v_mfma_f32_16x16x32_bf16 v[60:63], v[212:215], v[176:179], v[60:63]
	s_waitcnt lgkmcnt(0)
	s_barrier
	v_mfma_f32_16x16x32_bf16 v[64:67], v[200:203], v[184:187], v[64:67]
	v_mfma_f32_16x16x32_bf16 v[56:59], v[204:207], v[184:187], v[56:59]
	v_mfma_f32_16x16x32_bf16 v[52:55], v[208:211], v[184:187], v[52:55]
	v_mfma_f32_16x16x32_bf16 v[48:51], v[212:215], v[184:187], v[48:51]
	v_mfma_f32_16x16x32_bf16 v[44:47], v[200:203], v[188:191], v[44:47]
	v_mfma_f32_16x16x32_bf16 v[40:43], v[204:207], v[188:191], v[40:43]
	v_mfma_f32_16x16x32_bf16 v[36:39], v[208:211], v[188:191], v[36:39]
	v_mfma_f32_16x16x32_bf16 v[32:35], v[212:215], v[188:191], v[32:35]
	v_mfma_f32_16x16x32_bf16 v[28:31], v[200:203], v[192:195], v[28:31]
	v_mfma_f32_16x16x32_bf16 v[24:27], v[204:207], v[192:195], v[24:27]
	v_mfma_f32_16x16x32_bf16 v[20:23], v[208:211], v[192:195], v[20:23]
	v_mfma_f32_16x16x32_bf16 v[16:19], v[212:215], v[192:195], v[16:19]
	v_mfma_f32_16x16x32_bf16 v[12:15], v[200:203], v[196:199], v[12:15]
	v_mfma_f32_16x16x32_bf16 v[8:11], v[204:207], v[196:199], v[8:11]
	v_mfma_f32_16x16x32_bf16 v[4:7], v[208:211], v[196:199], v[4:7]
	v_mfma_f32_16x16x32_bf16 v[0:3], v[212:215], v[196:199], v[0:3]
	s_mov_b32 s24, s18
	s_mov_b32 s18, s25
	s_mov_b32 s25, s32
	s_mov_b32 s32, s24
	s_add_i32 s0, s87, s80
	s_cmp_gt_i32 s0, 63
	s_cselect_b32 s1, s79, 0
	s_cselect_b32 s87, s29, s0
	s_add_i32 s78, s1, s78
	s_max_i32 s0, s87, s78
	s_cmp_gt_i32 s0, 63
	s_cselect_b64 s[70:71], -1, 0
	s_cmp_lt_i32 s0, 64
	s_cbranch_scc0 .LBB0_104
	s_lshl_b32 s0, s78, 1
	s_and_b32 s0, s0, 0xfffff8
	s_and_b32 s1, s87, 7
	s_or_b32 s0, s0, s1
	s_lshl_b32 s1, s78, 3
	s_and_b32 s1, s1, 24
	s_lshr_b32 s24, s87, 3
	s_add_i32 s1, s1, s24
	v_lshl_add_u32 v132, s0, 8, v142
	v_ashrrev_i32_e32 v133, 31, v132
	v_lshl_add_u32 v134, s1, 7, v142
	v_lshlrev_b64 v[132:133], 11, v[132:133]
	v_ashrrev_i32_e32 v135, 31, v134
	v_lshl_add_u64 v[132:133], s[50:51], 0, v[132:133]
	v_mov_b32_e32 v131, v129
	v_lshlrev_b64 v[134:135], 11, v[134:135]
	v_readfirstlane_b32 s0, v144
	v_lshl_add_u64 v[132:133], v[132:133], 0, v[130:131]
	v_lshl_add_u64 v[134:135], s[4:5], 0, v[134:135]
	s_mov_b32 m0, s0
	v_readfirstlane_b32 s0, v143
	v_lshl_add_u64 v[130:131], v[134:135], 0, v[130:131]
	global_load_lds_dwordx4 v[132:133], off
	v_lshl_add_u64 v[134:135], v[132:133], 0, s[6:7]
	s_mov_b32 m0, s0
	v_readfirstlane_b32 s0, v139
	global_load_lds_dwordx4 v[134:135], off
	v_lshl_add_u64 v[134:135], v[132:133], 0, s[8:9]
	s_mov_b32 m0, s0
	v_readfirstlane_b32 s0, v138
	global_load_lds_dwordx4 v[134:135], off
	v_lshl_add_u64 v[132:133], v[132:133], 0, s[10:11]
	s_mov_b32 m0, s0
	v_readfirstlane_b32 s0, v137
	global_load_lds_dwordx4 v[132:133], off
	s_mov_b32 m0, s0
	v_readfirstlane_b32 s0, v136
	global_load_lds_dwordx4 v[130:131], off
	v_lshl_add_u64 v[130:131], v[130:131], 0, s[6:7]
	s_mov_b32 m0, s0
	s_nop 0
	global_load_lds_dwordx4 v[130:131], off

	.amdhsa_kernel _Z14fwd_megakernel6Params
		.amdhsa_group_segment_fixed_size 73728
		.amdhsa_private_segment_fixed_size 0
		.amdhsa_kernarg_size 392
		.amdhsa_user_sgpr_count 2
		.amdhsa_user_sgpr_dispatch_ptr 0
		.amdhsa_user_sgpr_queue_ptr 0
		.amdhsa_user_sgpr_kernarg_segment_ptr 1
		.amdhsa_user_sgpr_dispatch_id 0
		.amdhsa_user_sgpr_kernarg_preload_length 0
		.amdhsa_user_sgpr_kernarg_preload_offset 0
		.amdhsa_user_sgpr_private_segment_size 0
		.amdhsa_uses_dynamic_stack 0
		.amdhsa_enable_private_segment 0
		.amdhsa_system_sgpr_workgroup_id_x 1
		.amdhsa_system_sgpr_workgroup_id_y 0
		.amdhsa_system_sgpr_workgroup_id_z 0
		.amdhsa_system_sgpr_workgroup_info 0
		.amdhsa_system_vgpr_workitem_id 2
		.amdhsa_next_free_vgpr 245
		.amdhsa_next_free_sgpr 98
		.amdhsa_accum_offset 248
		.amdhsa_reserve_vcc 1
		.amdhsa_float_round_mode_32 0
		.amdhsa_float_round_mode_16_64 0
		.amdhsa_float_denorm_mode_32 3
		.amdhsa_float_denorm_mode_16_64 3
		.amdhsa_dx10_clamp 1
		.amdhsa_ieee_mode 1
		.amdhsa_fp16_overflow 0
		.amdhsa_tg_split 0
		.amdhsa_exception_fp_ieee_invalid_op 0
		.amdhsa_exception_fp_denorm_src 0
		.amdhsa_exception_fp_ieee_div_zero 0
		.amdhsa_exception_fp_ieee_overflow 0
		.amdhsa_exception_fp_ieee_underflow 0
		.amdhsa_exception_fp_ieee_inexact 0
		.amdhsa_exception_int_div_zero 0
	.end_amdhsa_kernel

amdhsa.kernels:
  - .agpr_count:     0
    .args:
      - .offset:         0
        .size:           136
        .value_kind:     by_value
      - .offset:         136
        .size:           4
        .value_kind:     hidden_block_count_x
      - .offset:         140
        .size:           4
        .value_kind:     hidden_block_count_y
      - .offset:         144
        .size:           4
        .value_kind:     hidden_block_count_z
      - .offset:         148
        .size:           2
        .value_kind:     hidden_group_size_x
      - .offset:         150
        .size:           2
        .value_kind:     hidden_group_size_y
      - .offset:         152
        .size:           2
        .value_kind:     hidden_group_size_z
      - .offset:         154
        .size:           2
        .value_kind:     hidden_remainder_x
      - .offset:         156
        .size:           2
        .value_kind:     hidden_remainder_y
      - .offset:         158
        .size:           2
        .value_kind:     hidden_remainder_z
      - .offset:         176
        .size:           8
        .value_kind:     hidden_global_offset_x
      - .offset:         184
        .size:           8
        .value_kind:     hidden_global_offset_y
      - .offset:         192
        .size:           8
        .value_kind:     hidden_global_offset_z
      - .offset:         200
        .size:           2
        .value_kind:     hidden_grid_dims
      - .offset:         224
        .size:           8
        .value_kind:     hidden_multigrid_sync_arg
    .group_segment_fixed_size: 73728
    .kernarg_segment_align: 8
    .kernarg_segment_size: 392
    .language:       OpenCL C
    .language_version:
      - 2
      - 0
    .max_flat_workgroup_size: 256
    .name:           _Z14fwd_megakernel6Params
    .private_segment_fixed_size: 0
    .sgpr_count:     104
    .sgpr_spill_count: 6
    .symbol:         _Z14fwd_megakernel6Params.kd
    .uniform_work_group_size: 1
    .uses_dynamic_stack: false
    .vgpr_count:     245
    .vgpr_spill_count: 0
    .wavefront_size: 64
